# attention: end-of-PV wait leaves the two MIX stores in flight (vmcnt(2)); plus P2 pooling/attention order swap for half the workgroups
# baseline (speedup 1.0000x reference)
; #define LAS __attribute__((address_space(3)))
; __host__ __device__ __forceinline__ size_t tl_off(int row, int k, int K) { return ((((size_t)(row >> 4) * (size_t)(K >> 5)) + (size_t)(k >> 5)) << 9) + (size_t)((row & 15) * 32 + (k & 31)); }
; __device__ __forceinline__ void p2_attention(Frame& F, const bf16_t* Qg, const bf16_t* Kg, const bf16_t* Vg, bf16_t* MIX) {
;     ...
; #pragma unroll
;             for (int jb = 0; jb < 2; ++jb) {
;                 const int o = 8 * jb, cq = 32 * u.jh + 16 * jb + q;
;                 f32x4 ov[4];
; #pragma unroll
;                 for (int n = 0; n < 4; ++n) ov[n] = (f32x4){0.f, 0.f, 0.f, 0.f};
;                 {
;                     const int qr = q >> 2, p = lane & 3;
;                     const int fv = (((qr >> 1) & 1) << 1) | (((jb + g) & 1) << 2);
;                     const LAS unsigned char* vb = lds + AT_B + (wbase * 40 + o + 8 * g + qr) * 128 + (p >> 1) * 16 + (p & 1) * 8;
;                     const LAS unsigned char* vn[4];
; #pragma unroll
;                     for (int n = 0; n < 4; ++n) vn[n] = vb + ((2 * n) ^ fv) * 16;
; #pragma unroll
;                     for (int wl = 0; wl < 8; ++wl) {
;                         const bf16x8 pf = __builtin_bit_cast(bf16x8, pw[jb][wl]);
; #pragma unroll
;                         for (int n = 0; n < 4; ++n) {
;                             const s16x4 lo = __builtin_bit_cast(s16x4, __builtin_amdgcn_ds_read_tr16_b64_v4i16((LAS s16x4*)(vn[n] + wl * 5120)));
;                             const s16x4 hi = __builtin_bit_cast(s16x4, __builtin_amdgcn_ds_read_tr16_b64_v4i16((LAS s16x4*)(vn[n] + wl * 5120 + 512)));
;                             const bf16x8 vf = (bf16x8){lo[0], lo[1], lo[2], lo[3], hi[0], hi[1], hi[2], hi[3]};
;                             ov[n] = __builtin_amdgcn_mfma_f32_16x16x32_bf16(vf, pf, ov[n], 0, 0, 0);
;                         }
;                     }
;                 }
;                 unsigned char* op = (unsigned char*)MIX + (size_t)tl_off(u.b * SEQ + r * 64 + cq, 32 * u.h, KMIX) * 2 + 16 * g;
;                 const float il8 = 8.f * il[jb];
.LBB0_284:
	v_or_b32_e32 v84, v96, v164
	v_lshlrev_b32_e32 v96, 7, v84
	v_add_u32_e32 v189, v175, v96
	v_add_u32_e32 v218, v189, v176
	ds_read_b64_tr_b16 v[84:85], v218
	ds_read_b64_tr_b16 v[86:87], v218 offset:512
	v_add_u32_e32 v219, v189, v177
	v_add_u32_e32 v220, v189, v178
	ds_read_b64_tr_b16 v[88:89], v218 offset:36352
	ds_read_b64_tr_b16 v[90:91], v219
	ds_read_b64_tr_b16 v[92:93], v219 offset:512
	ds_read_b64_tr_b16 v[94:95], v219 offset:36352
	ds_read_b64_tr_b16 v[190:191], v220
	ds_read_b64_tr_b16 v[192:193], v220 offset:512
	v_add_u32_e32 v189, v189, v179
	ds_read_b64_tr_b16 v[194:195], v220 offset:36352
	ds_read_b64_tr_b16 v[196:197], v189
	ds_read_b64_tr_b16 v[198:199], v189 offset:512
	ds_read_b64_tr_b16 v[200:201], v189 offset:36352
	s_waitcnt lgkmcnt(10)
	v_mfma_f32_16x16x32_bf16 v[84:87], v[84:87], v[16:19], 0
	s_lshl_b32 s6, s92, 12
	s_lshl_b32 s7, s96, 6
	s_add_i32 s7, s7, s6
	s_waitcnt lgkmcnt(7)
	v_mfma_f32_16x16x32_bf16 v[90:93], v[90:93], v[16:19], 0
	s_or_b32 s6, s7, s97
	s_ashr_i32 s8, s6, 4
	s_mul_i32 s6, s8, 24
	s_waitcnt lgkmcnt(4)
	v_mfma_f32_16x16x32_bf16 v[190:193], v[190:193], v[16:19], 0
	s_mul_hi_i32 s7, s8, 24
	s_or_b32 s6, s6, s89
	s_lshl_b64 s[6:7], s[6:7], 10
	s_waitcnt lgkmcnt(1)
	v_mfma_f32_16x16x32_bf16 v[16:19], v[196:199], v[16:19], 0
	ds_read_b64_tr_b16 v[196:197], v218 offset:5120
	ds_read_b64_tr_b16 v[198:199], v218 offset:5632
	ds_read_b64_tr_b16 v[202:203], v218 offset:10240
	ds_read_b64_tr_b16 v[204:205], v218 offset:10752
	s_add_i32 s94, s94, 4
	s_mov_b32 s92, s0
	s_waitcnt lgkmcnt(2)
	v_mfma_f32_16x16x32_bf16 v[84:87], v[196:199], v[20:23], v[84:87]
	ds_read_b64_tr_b16 v[196:197], v219 offset:5120
	ds_read_b64_tr_b16 v[198:199], v219 offset:5632
	ds_read_b64_tr_b16 v[206:207], v219 offset:10240
	ds_read_b64_tr_b16 v[208:209], v219 offset:10752
	s_waitcnt lgkmcnt(2)
	v_mfma_f32_16x16x32_bf16 v[90:93], v[196:199], v[20:23], v[90:93]
	ds_read_b64_tr_b16 v[196:197], v220 offset:5120
	ds_read_b64_tr_b16 v[198:199], v220 offset:5632
	ds_read_b64_tr_b16 v[210:211], v220 offset:10240
	ds_read_b64_tr_b16 v[212:213], v220 offset:10752
	s_waitcnt lgkmcnt(2)
	v_mfma_f32_16x16x32_bf16 v[190:193], v[196:199], v[20:23], v[190:193]
	ds_read_b64_tr_b16 v[196:197], v189 offset:5120
	ds_read_b64_tr_b16 v[198:199], v189 offset:5632
	ds_read_b64_tr_b16 v[214:215], v189 offset:10240
	ds_read_b64_tr_b16 v[216:217], v189 offset:10752
	s_waitcnt lgkmcnt(2)
	v_mfma_f32_16x16x32_bf16 v[16:19], v[196:199], v[20:23], v[16:19]
	v_mfma_f32_16x16x32_bf16 v[20:23], v[202:205], v[24:27], v[84:87]
	v_mfma_f32_16x16x32_bf16 v[84:87], v[206:209], v[24:27], v[90:93]
	v_mfma_f32_16x16x32_bf16 v[90:93], v[210:213], v[24:27], v[190:193]
	s_waitcnt lgkmcnt(0)
	v_mfma_f32_16x16x32_bf16 v[16:19], v[214:217], v[24:27], v[16:19]
	ds_read_b64_tr_b16 v[24:25], v218 offset:15360
	ds_read_b64_tr_b16 v[26:27], v218 offset:15872
	ds_read_b64_tr_b16 v[190:191], v218 offset:20480
	ds_read_b64_tr_b16 v[192:193], v218 offset:20992
	s_waitcnt lgkmcnt(2)
	v_mfma_f32_16x16x32_bf16 v[20:23], v[24:27], v[28:31], v[20:23]
	ds_read_b64_tr_b16 v[24:25], v219 offset:15360
	ds_read_b64_tr_b16 v[26:27], v219 offset:15872
	ds_read_b64_tr_b16 v[196:197], v219 offset:20480
	ds_read_b64_tr_b16 v[198:199], v219 offset:20992
	s_waitcnt lgkmcnt(2)
	v_mfma_f32_16x16x32_bf16 v[24:27], v[24:27], v[28:31], v[84:87]
	s_nop 2
	ds_read_b64_tr_b16 v[84:85], v220 offset:15360
	ds_read_b64_tr_b16 v[86:87], v220 offset:15872
	ds_read_b64_tr_b16 v[202:203], v220 offset:20480
	ds_read_b64_tr_b16 v[204:205], v220 offset:20992
	s_waitcnt lgkmcnt(2)
	v_mfma_f32_16x16x32_bf16 v[84:87], v[84:87], v[28:31], v[90:93]
	s_nop 2
	ds_read_b64_tr_b16 v[90:91], v189 offset:15360
	ds_read_b64_tr_b16 v[92:93], v189 offset:15872
	ds_read_b64_tr_b16 v[206:207], v189 offset:20480
	ds_read_b64_tr_b16 v[208:209], v189 offset:20992
	s_waitcnt lgkmcnt(2)
	v_mfma_f32_16x16x32_bf16 v[16:19], v[90:93], v[28:31], v[16:19]
	ds_read_b64_tr_b16 v[28:29], v218 offset:25600
	ds_read_b64_tr_b16 v[30:31], v218 offset:26112
	v_mfma_f32_16x16x32_bf16 v[20:23], v[190:193], v[36:39], v[20:23]
	v_mfma_f32_16x16x32_bf16 v[24:27], v[196:199], v[36:39], v[24:27]
	v_mfma_f32_16x16x32_bf16 v[196:199], v[202:205], v[36:39], v[84:87]
	s_nop 2
	ds_read_b64_tr_b16 v[86:87], v218 offset:35840
	ds_read_b64_tr_b16 v[190:191], v219 offset:25600
	ds_read_b64_tr_b16 v[192:193], v219 offset:26112
	s_waitcnt lgkmcnt(5)
	v_mfma_f32_16x16x32_bf16 v[36:39], v[206:209], v[36:39], v[16:19]
	s_nop 2
	ds_read_b64_tr_b16 v[16:17], v220 offset:25600
	ds_read_b64_tr_b16 v[18:19], v220 offset:26112
	ds_read_b64_tr_b16 v[202:203], v218 offset:30720
	ds_read_b64_tr_b16 v[204:205], v218 offset:31232
	s_waitcnt lgkmcnt(7)
	v_mfma_f32_16x16x32_bf16 v[20:23], v[28:31], v[32:35], v[20:23]
	ds_read_b64_tr_b16 v[92:93], v219 offset:35840
	ds_read_b64_tr_b16 v[28:29], v219 offset:30720
	ds_read_b64_tr_b16 v[30:31], v219 offset:31232
	s_waitcnt lgkmcnt(5)
	v_mfma_f32_16x16x32_bf16 v[210:213], v[16:19], v[32:35], v[196:199]
	v_add_f32_e32 v16, v82, v83
	v_rcp_f32_e32 v90, v16
	s_waitcnt lgkmcnt(3)
	v_mfma_f32_16x16x32_bf16 v[16:19], v[202:205], v[40:43], v[20:23]
	v_mfma_f32_16x16x32_bf16 v[24:27], v[190:193], v[32:35], v[24:27]
	ds_read_b64_tr_b16 v[192:193], v220 offset:35840
	ds_read_b64_tr_b16 v[206:207], v220 offset:30720
	ds_read_b64_tr_b16 v[208:209], v220 offset:31232
	ds_read_b64_tr_b16 v[198:199], v189 offset:35840
	ds_read_b64_tr_b16 v[20:21], v189 offset:25600
	ds_read_b64_tr_b16 v[22:23], v189 offset:26112
	ds_read_b64_tr_b16 v[82:83], v189 offset:30720
	ds_read_b64_tr_b16 v[84:85], v189 offset:31232
	v_mfma_f32_16x16x32_bf16 v[16:19], v[86:89], v[44:47], v[16:19]
	v_mul_f32_e32 v86, 0x41000000, v90
	s_waitcnt lgkmcnt(8)
; #define LAS __attribute__((address_space(3)))
; __device__ __forceinline__ void p2_attention(Frame& F, const bf16_t* Qg, const bf16_t* Kg, const bf16_t* Vg, bf16_t* MIX) {
;     ...
;             for (int jb = 0; jb < 2; ++jb) {
;                 const int o = 8 * jb, cq = 32 * u.jh + 16 * jb + q;
;                 f32x4 ov[4];
; #pragma unroll
;                 for (int n = 0; n < 4; ++n) ov[n] = (f32x4){0.f, 0.f, 0.f, 0.f};
;                 {
;                     const int qr = q >> 2, p = lane & 3;
;                     const int fv = (((qr >> 1) & 1) << 1) | (((jb + g) & 1) << 2);
;                     const LAS unsigned char* vb = lds + AT_B + (wbase * 40 + o + 8 * g + qr) * 128 + (p >> 1) * 16 + (p & 1) * 8;
;                     const LAS unsigned char* vn[4];
; #pragma unroll
;                     for (int n = 0; n < 4; ++n) vn[n] = vb + ((2 * n) ^ fv) * 16;
; #pragma unroll
;                     for (int wl = 0; wl < 8; ++wl) {
;                         const bf16x8 pf = __builtin_bit_cast(bf16x8, pw[jb][wl]);
; #pragma unroll
;                         for (int n = 0; n < 4; ++n) {
;                             const s16x4 lo = __builtin_bit_cast(s16x4, __builtin_amdgcn_ds_read_tr16_b64_v4i16((LAS s16x4*)(vn[n] + wl * 5120)));
;                             const s16x4 hi = __builtin_bit_cast(s16x4, __builtin_amdgcn_ds_read_tr16_b64_v4i16((LAS s16x4*)(vn[n] + wl * 5120 + 512)));
;                             const bf16x8 vf = (bf16x8){lo[0], lo[1], lo[2], lo[3], hi[0], hi[1], hi[2], hi[3]};
;                             ov[n] = __builtin_amdgcn_mfma_f32_16x16x32_bf16(vf, pf, ov[n], 0, 0, 0);
;                         }
;                     }
;                 }
;                 unsigned char* op = (unsigned char*)MIX + (size_t)tl_off(u.b * SEQ + r * 64 + cq, 32 * u.h, KMIX) * 2 + 16 * g;
;                 const float il8 = 8.f * il[jb];
;                 unsigned a0 = pk4_fp8(ov[0][0] * il8, ov[0][1] * il8, ov[0][2] * il8, ov[0][3] * il8), a1 = pk4_fp8(ov[1][0] * il8, ov[1][1] * il8, ov[1][2] * il8, ov[1][3] * il8);
;                 unsigned a2 = pk4_fp8(ov[2][0] * il8, ov[2][1] * il8, ov[2][2] * il8, ov[2][3] * il8), a3 = pk4_fp8(ov[3][0] * il8, ov[3][1] * il8, ov[3][2] * il8, ov[3][3] * il8);
	v_mfma_f32_16x16x32_bf16 v[24:27], v[28:31], v[40:43], v[24:27]
	v_mfma_f32_16x16x32_bf16 v[24:27], v[92:95], v[44:47], v[24:27]
	s_nop 3
	v_mul_f32_e32 v87, v86, v16
	v_mul_f32_e32 v17, v86, v17
	v_mov_b32_e32 v16, v97
	v_cvt_pk_fp8_f32 v16, v87, v17
	v_mul_f32_e32 v18, v86, v18
	v_mul_f32_e32 v17, v86, v19
	v_mul_f32_e32 v24, v86, v24
	v_cvt_pk_fp8_f32 v16, v18, v17 op_sel:[0,0,1]
	s_waitcnt lgkmcnt(2)
	v_mfma_f32_16x16x32_bf16 v[18:21], v[20:23], v[32:35], v[36:39]
	v_mul_f32_e32 v22, v86, v25
	v_mov_b32_e32 v17, v97
	v_cvt_pk_fp8_f32 v17, v24, v22
	v_mfma_f32_16x16x32_bf16 v[22:25], v[206:209], v[40:43], v[210:213]
	v_mul_f32_e32 v26, v86, v26
	v_mul_f32_e32 v27, v86, v27
	v_cvt_pk_fp8_f32 v17, v26, v27 op_sel:[0,0,1]
	v_mfma_f32_16x16x32_bf16 v[22:25], v[192:195], v[44:47], v[22:25]
	v_add_u32_e32 v36, v180, v96
	v_add_u32_e32 v94, v36, v181
	v_add_u32_e32 v95, v36, v182
	v_add_u32_e32 v96, v36, v183
	v_add_u32_e32 v189, v36, v184
	s_nop 2
	v_mul_f32_e32 v26, v86, v22
	v_mul_f32_e32 v27, v86, v23
	s_waitcnt lgkmcnt(0)
	v_mfma_f32_16x16x32_bf16 v[20:23], v[82:85], v[40:43], v[18:21]
	v_mul_f32_e32 v24, v86, v24
	v_mul_f32_e32 v25, v86, v25
	v_mfma_f32_16x16x32_bf16 v[20:23], v[198:201], v[44:47], v[20:23]
	v_mov_b32_e32 v18, v97
	v_mov_b32_e32 v19, v97
	v_cvt_pk_fp8_f32 v18, v26, v27
	v_cvt_pk_fp8_f32 v18, v24, v25 op_sel:[0,0,1]
	s_nop 3
	v_mul_f32_e32 v20, v86, v20
	v_mul_f32_e32 v21, v86, v21
	v_cvt_pk_fp8_f32 v19, v20, v21
	v_mul_f32_e32 v20, v86, v22
	v_mul_f32_e32 v21, v86, v23
	v_cvt_pk_fp8_f32 v19, v20, v21 op_sel:[0,0,1]
	s_nop 0
	s_nop 1
	v_permlane32_swap_b32 v16, v18
	v_permlane32_swap_b32 v17, v19
	s_nop 1
	v_permlane16_swap_b32 v16, v17
	v_permlane16_swap_b32 v18, v19
	s_nop 1
	ds_read_b64_tr_b16 v[20:21], v94
	ds_read_b64_tr_b16 v[22:23], v94 offset:512
	ds_read_b64_tr_b16 v[24:25], v94 offset:36352
	ds_read_b64_tr_b16 v[26:27], v95
	ds_read_b64_tr_b16 v[28:29], v95 offset:512
	ds_read_b64_tr_b16 v[30:31], v95 offset:36352
	ds_read_b64_tr_b16 v[32:33], v96
	ds_read_b64_tr_b16 v[34:35], v96 offset:512
	ds_read_b64_tr_b16 v[36:37], v96 offset:36352
	ds_read_b64_tr_b16 v[38:39], v189
	ds_read_b64_tr_b16 v[40:41], v189 offset:512
	ds_read_b64_tr_b16 v[42:43], v189 offset:36352
	s_waitcnt lgkmcnt(10)
	v_mfma_f32_16x16x32_bf16 v[20:23], v[20:23], v[48:51], 0
	s_waitcnt lgkmcnt(7)
	v_mfma_f32_16x16x32_bf16 v[26:29], v[26:29], v[48:51], 0
	s_waitcnt lgkmcnt(4)
	v_mfma_f32_16x16x32_bf16 v[32:35], v[32:35], v[48:51], 0
	s_waitcnt lgkmcnt(1)
	v_mfma_f32_16x16x32_bf16 v[38:41], v[38:41], v[48:51], 0
	ds_read_b64_tr_b16 v[44:45], v94 offset:5120
	ds_read_b64_tr_b16 v[46:47], v94 offset:5632
	ds_read_b64_tr_b16 v[48:49], v94 offset:10240
	ds_read_b64_tr_b16 v[50:51], v94 offset:10752
	s_waitcnt lgkmcnt(2)
	v_mfma_f32_16x16x32_bf16 v[20:23], v[44:47], v[52:55], v[20:23]
	ds_read_b64_tr_b16 v[44:45], v95 offset:5120
	ds_read_b64_tr_b16 v[46:47], v95 offset:5632
	ds_read_b64_tr_b16 v[82:83], v95 offset:10240
	ds_read_b64_tr_b16 v[84:85], v95 offset:10752
	s_waitcnt lgkmcnt(2)
	v_mfma_f32_16x16x32_bf16 v[26:29], v[44:47], v[52:55], v[26:29]
	ds_read_b64_tr_b16 v[44:45], v96 offset:5120
	ds_read_b64_tr_b16 v[46:47], v96 offset:5632
	ds_read_b64_tr_b16 v[86:87], v96 offset:10240
	ds_read_b64_tr_b16 v[88:89], v96 offset:10752
	s_waitcnt lgkmcnt(2)
	v_mfma_f32_16x16x32_bf16 v[32:35], v[44:47], v[52:55], v[32:35]
	ds_read_b64_tr_b16 v[44:45], v189 offset:5120
	ds_read_b64_tr_b16 v[46:47], v189 offset:5632
	ds_read_b64_tr_b16 v[90:91], v189 offset:10240
	ds_read_b64_tr_b16 v[92:93], v189 offset:10752
	v_mfma_f32_16x16x32_bf16 v[20:23], v[48:51], v[56:59], v[20:23]
	s_waitcnt lgkmcnt(2)
	v_mfma_f32_16x16x32_bf16 v[38:41], v[44:47], v[52:55], v[38:41]
	ds_read_b64_tr_b16 v[44:45], v94 offset:15360
	ds_read_b64_tr_b16 v[46:47], v94 offset:15872
	ds_read_b64_tr_b16 v[48:49], v94 offset:20480
	ds_read_b64_tr_b16 v[50:51], v94 offset:20992
	v_mfma_f32_16x16x32_bf16 v[26:29], v[82:85], v[56:59], v[26:29]
	s_waitcnt lgkmcnt(2)
	v_mfma_f32_16x16x32_bf16 v[20:23], v[44:47], v[60:63], v[20:23]
	ds_read_b64_tr_b16 v[44:45], v95 offset:15360
	ds_read_b64_tr_b16 v[46:47], v95 offset:15872
	ds_read_b64_tr_b16 v[52:53], v95 offset:20480
	ds_read_b64_tr_b16 v[54:55], v95 offset:20992
	v_mfma_f32_16x16x32_bf16 v[32:35], v[86:89], v[56:59], v[32:35]
	v_mfma_f32_16x16x32_bf16 v[38:41], v[90:93], v[56:59], v[38:41]
	s_waitcnt lgkmcnt(2)
	v_mfma_f32_16x16x32_bf16 v[26:29], v[44:47], v[60:63], v[26:29]
	ds_read_b64_tr_b16 v[44:45], v96 offset:15360
	ds_read_b64_tr_b16 v[46:47], v96 offset:15872
	ds_read_b64_tr_b16 v[56:57], v96 offset:20480
	ds_read_b64_tr_b16 v[58:59], v96 offset:20992
	s_waitcnt lgkmcnt(2)
; __host__ __device__ __forceinline__ size_t tl_off(int row, int k, int K) { return ((((size_t)(row >> 4) * (size_t)(K >> 5)) + (size_t)(k >> 5)) << 9) + (size_t)((row & 15) * 32 + (k & 31)); }
; #define ATT_WAIT_BAR() do { asm volatile("s_waitcnt vmcnt(0) lgkmcnt(0)" ::: "memory"); __builtin_amdgcn_s_barrier(); asm volatile("" ::: "memory"); } while (0)
; template <int KIND> __device__ __forceinline__ void attn_dma(unsigned dst, const bf16_t* src, const AttnUnit& u, int wid, int lane) {
;     const int np = u.nrows * 5;
;     const char* base = (const char*)(src + ((size_t)(u.b * NHEAD + u.h) * SEQ + u.krow_lo * 64 + 24 * u.jh) * HD);
; #pragma unroll
;     for (int it = 0; it < 10; ++it) {
;         const int pi = it * 8 + wid;
;         if (pi < np) {
;             const int w = (pi * 205) >> 10, p = pi - 5 * w, c = 8 * p + (lane >> 3);
;             const int sw = (KIND == 0) ? (((c >> 1) & 1) | (((c >> 3) & 3) << 1)) : ((((c >> 1) & 1) << 1) | (((c >> 3) & 1) << 2));
;             const int ch = (lane & 7) ^ sw;
;             const char* gp = base + (w * 64 + c) * (HD * 2) + ch * 16;
;             glds16(gp, (unsigned)__builtin_amdgcn_readfirstlane(dst + pi * 1024));
; __device__ __forceinline__ void p2_attention(Frame& F, const bf16_t* Qg, const bf16_t* Kg, const bf16_t* Vg, bf16_t* MIX) {
;     ...
;                 unsigned char* op = (unsigned char*)MIX + (size_t)tl_off(u.b * SEQ + r * 64 + cq, 32 * u.h, KMIX) * 2 + 16 * g;
;                 const float il8 = 8.f * il[jb];
;                 unsigned a0 = pk4_fp8(ov[0][0] * il8, ov[0][1] * il8, ov[0][2] * il8, ov[0][3] * il8), a1 = pk4_fp8(ov[1][0] * il8, ov[1][1] * il8, ov[1][2] * il8, ov[1][3] * il8);
;                 unsigned a2 = pk4_fp8(ov[2][0] * il8, ov[2][1] * il8, ov[2][2] * il8, ov[2][3] * il8), a3 = pk4_fp8(ov[3][0] * il8, ov[3][1] * il8, ov[3][2] * il8, ov[3][3] * il8);
;                 asm volatile("s_nop 1\n\tv_permlane32_swap_b32 %0, %2\n\tv_permlane32_swap_b32 %1, %3\n\ts_nop 1\n\tv_permlane16_swap_b32 %0, %1\n\tv_permlane16_swap_b32 %2, %3\n\ts_nop 1" : "+v"(a0), "+v"(a1), "+v"(a2), "+v"(a3));
;                 *(u32x4*)op = (u32x4){a0, a1, a2, a3};
;             }
;             ATT_WAIT_BAR();
;             u = un;
; #pragma unroll
;             for (int jb = 0; jb < 2; ++jb) { qf[jb][0] = nq[jb][0]; qf[jb][1] = nq[jb][1]; }
	v_mfma_f32_16x16x32_bf16 v[32:35], v[44:47], v[60:63], v[32:35]
	ds_read_b64_tr_b16 v[44:45], v189 offset:15360
	ds_read_b64_tr_b16 v[46:47], v189 offset:15872
	ds_read_b64_tr_b16 v[82:83], v189 offset:20480
	ds_read_b64_tr_b16 v[84:85], v189 offset:20992
	v_mfma_f32_16x16x32_bf16 v[20:23], v[48:51], v[64:67], v[20:23]
	s_waitcnt lgkmcnt(2)
	v_mfma_f32_16x16x32_bf16 v[38:41], v[44:47], v[60:63], v[38:41]
	ds_read_b64_tr_b16 v[44:45], v94 offset:25600
	ds_read_b64_tr_b16 v[46:47], v94 offset:26112
	ds_read_b64_tr_b16 v[48:49], v94 offset:30720
	ds_read_b64_tr_b16 v[50:51], v94 offset:31232
	v_mfma_f32_16x16x32_bf16 v[26:29], v[52:55], v[64:67], v[26:29]
	s_waitcnt lgkmcnt(2)
	v_mfma_f32_16x16x32_bf16 v[44:47], v[44:47], v[68:71], v[20:23]
	s_nop 2
	ds_read_b64_tr_b16 v[20:21], v95 offset:25600
	ds_read_b64_tr_b16 v[22:23], v95 offset:26112
	ds_read_b64_tr_b16 v[52:53], v95 offset:30720
	ds_read_b64_tr_b16 v[54:55], v95 offset:31232
	v_mfma_f32_16x16x32_bf16 v[32:35], v[56:59], v[64:67], v[32:35]
	s_waitcnt lgkmcnt(2)
	v_mfma_f32_16x16x32_bf16 v[56:59], v[20:23], v[68:71], v[26:29]
	ds_read_b64_tr_b16 v[20:21], v96 offset:25600
	ds_read_b64_tr_b16 v[22:23], v96 offset:26112
	ds_read_b64_tr_b16 v[60:61], v96 offset:30720
	ds_read_b64_tr_b16 v[62:63], v96 offset:31232
	v_mfma_f32_16x16x32_bf16 v[38:41], v[82:85], v[64:67], v[38:41]
	s_waitcnt lgkmcnt(2)
	v_mfma_f32_16x16x32_bf16 v[64:67], v[20:23], v[68:71], v[32:35]
	ds_read_b64_tr_b16 v[20:21], v189 offset:25600
	ds_read_b64_tr_b16 v[22:23], v189 offset:26112
	ds_read_b64_tr_b16 v[82:83], v189 offset:30720
	ds_read_b64_tr_b16 v[84:85], v189 offset:31232
	s_waitcnt lgkmcnt(2)
	v_mfma_f32_16x16x32_bf16 v[68:71], v[20:23], v[68:71], v[38:41]
	ds_read_b64_tr_b16 v[22:23], v94 offset:35840
	ds_read_b64_tr_b16 v[28:29], v95 offset:35840
	v_add_f32_e32 v20, v80, v81
	v_rcp_f32_e32 v32, v20
	v_mfma_f32_16x16x32_bf16 v[44:47], v[48:51], v[72:75], v[44:47]
	ds_read_b64_tr_b16 v[34:35], v96 offset:35840
	ds_read_b64_tr_b16 v[40:41], v189 offset:35840
	v_mul_f32_e32 v32, 0x41000000, v32
	v_mfma_f32_16x16x32_bf16 v[48:51], v[52:55], v[72:75], v[56:59]
	s_waitcnt lgkmcnt(3)
	v_mfma_f32_16x16x32_bf16 v[20:23], v[22:25], v[76:79], v[44:47]
	v_lshl_add_u64 v[24:25], v[162:163], 0, s[6:7]
	global_store_dwordx4 v[24:25], v[16:19], off
	s_or_b32 s6, s8, 1
	v_mfma_f32_16x16x32_bf16 v[52:55], v[60:63], v[72:75], v[64:67]
	s_mul_hi_i32 s7, s6, 24
	s_nop 2
	v_mul_f32_e32 v33, v32, v20
	v_mul_f32_e32 v21, v32, v21
	s_waitcnt lgkmcnt(2)
	v_mfma_f32_16x16x32_bf16 v[16:19], v[28:31], v[76:79], v[48:51]
	v_mov_b32_e32 v20, v97
	v_cvt_pk_fp8_f32 v20, v33, v21
	v_mov_b32_e32 v21, v97
	v_mfma_f32_16x16x32_bf16 v[56:59], v[82:85], v[72:75], v[68:71]
	v_mul_f32_e32 v22, v32, v22
	s_nop 2
	v_mul_f32_e32 v16, v32, v16
	v_mul_f32_e32 v17, v32, v17
	s_waitcnt lgkmcnt(1)
	v_mfma_f32_16x16x32_bf16 v[24:27], v[34:37], v[76:79], v[52:55]
	v_cvt_pk_fp8_f32 v21, v16, v17
	v_mul_f32_e32 v23, v32, v23
	v_mul_f32_e32 v16, v32, v18
	s_waitcnt lgkmcnt(0)
	v_mfma_f32_16x16x32_bf16 v[28:31], v[40:43], v[76:79], v[56:59]
	v_mul_f32_e32 v17, v32, v19
	v_cvt_pk_fp8_f32 v20, v22, v23 op_sel:[0,0,1]
	v_cvt_pk_fp8_f32 v21, v16, v17 op_sel:[0,0,1]
	v_mul_f32_e32 v16, v32, v24
	v_mul_f32_e32 v17, v32, v25
	v_mov_b32_e32 v22, v97
	v_cvt_pk_fp8_f32 v22, v16, v17
	s_nop 0
	v_mul_f32_e32 v16, v32, v28
	v_mul_f32_e32 v17, v32, v29
	v_mov_b32_e32 v23, v97
	v_cvt_pk_fp8_f32 v23, v16, v17
	s_mul_i32 s6, s6, 24
	s_or_b32 s6, s6, s89
	v_mul_f32_e32 v18, v32, v26
	v_mul_f32_e32 v19, v32, v27
	v_mul_f32_e32 v16, v32, v30
	v_mul_f32_e32 v17, v32, v31
	s_lshl_b64 s[6:7], s[6:7], 10
	v_cvt_pk_fp8_f32 v22, v18, v19 op_sel:[0,0,1]
	v_cvt_pk_fp8_f32 v23, v16, v17 op_sel:[0,0,1]
	v_lshl_add_u64 v[16:17], v[162:163], 0, s[6:7]
	s_nop 1
	v_permlane32_swap_b32 v20, v22
	v_permlane32_swap_b32 v21, v23
	s_nop 1
	v_permlane16_swap_b32 v20, v21
	v_permlane16_swap_b32 v22, v23
	s_nop 1
	global_store_dwordx4 v[16:17], v[20:23], off
	s_waitcnt vmcnt(2) lgkmcnt(0)
	s_barrier
	v_add_co_u32_e64 v16, s[6:7], s93, 1
	s_nop 0
	v_readfirstlane_b32 s93, v16
	s_and_b64 vcc, exec, s[6:7]
	s_mov_b32 s89, s1
	s_cbranch_vccnz .LBB0_265
.LBB0_285:
	s_lshl_b32 s0, s92, 3
	s_or_b32 s6, s0, s89
	s_ashr_i32 s7, s6, 31
	s_lshl_b64 s[6:7], s[6:7], 12
	v_lshlrev_b32_e32 v96, 6, v188
	v_lshl_add_u64 v[16:17], s[6:7], 0, v[96:97]
	s_mul_i32 s0, s95, 24
	v_or_b32_e32 v16, s0, v16
	s_mul_i32 s1, s91, 5
	v_lshlrev_b64 v[16:17], 7, v[16:17]
	s_cmp_ge_i32 s85, s1
	v_lshl_add_u64 v[16:17], s[22:23], 0, v[16:17]
	s_waitcnt vmcnt(2)
	s_cbranch_scc0 .LBB0_307
	s_cmp_ge_i32 s43, s1
	s_cbranch_scc0 .LBB0_308
